# hgrn in-proj: sections 2 and 3 swapped in round order so the v section is written last (stays in the XCD's L2 for scan pass A, no wbl2 in between)
# speedup vs baseline: 1.0004x; 1.0004x over previous
.LBB0_321:
	s_lshl_b32 s3, s3, 3
	v_cvt_f32_u32_e32 v0, s3
	s_sub_i32 s9, 0, s3
	s_ashr_i32 s8, s10, 3
	s_add_i32 s8, s11, s8
	v_rcp_iflag_f32_e32 v0, v0
	s_abs_i32 s11, s8
	s_ashr_i32 s10, s8, 31
	v_mul_f32_e32 v0, 0x4f7ffffe, v0
	v_cvt_u32_f32_e32 v0, v0
	s_nop 0
	v_readfirstlane_b32 s12, v0
	s_mul_i32 s9, s9, s12
	s_mul_hi_u32 s9, s12, s9
	s_add_i32 s12, s12, s9
	s_mul_hi_u32 s9, s11, s12
	s_mul_i32 s12, s9, s3
	s_sub_i32 s11, s11, s12
	s_add_i32 s13, s9, 1
	s_sub_i32 s12, s11, s3
	s_cmp_ge_u32 s11, s3
	s_cselect_b32 s9, s13, s9
	s_cselect_b32 s11, s12, s11
	s_add_i32 s12, s9, 1
	s_cmp_ge_u32 s11, s3
	s_cselect_b32 s9, s12, s9
	s_xor_b32 s9, s9, s10
	s_sub_i32 s9, s9, s10
	s_lshl_b32 s10, s9, 3
	s_sub_i32 s2, s2, s10
	s_min_i32 s11, s2, 8
	s_sext_i32_i16 s2, s11
	v_cvt_f32_i32_e32 v0, s2
	s_mul_i32 s9, s9, s3
	s_sub_i32 s8, s8, s9
	s_sext_i32_i16 s3, s8
	v_cvt_f32_i32_e32 v1, s3
	v_rcp_iflag_f32_e32 v2, v0
	s_xor_b32 s2, s3, s2
	s_ashr_i32 s2, s2, 30
	s_or_b32 s9, s2, 1
	v_mul_f32_e32 v2, v1, v2
	v_trunc_f32_e32 v2, v2
	v_fma_f32 v1, -v2, v0, v1
	v_cvt_i32_f32_e32 v2, v2
	v_cmp_ge_f32_e64 s[2:3], |v1|, |v0|
	s_and_b64 s[2:3], s[2:3], exec
	s_cselect_b32 s2, s9, 0
	v_readfirstlane_b32 s3, v2
	s_add_i32 s2, s3, s2
	s_mul_i32 s3, s2, s11
	s_sub_i32 s3, s8, s3
	s_sext_i32_i16 s3, s3
	s_add_i32 s38, s10, s3
	s_and_b64 s[8:9], s[6:7], exec
	s_cselect_b32 s29, s86, 5
	s_cselect_b32 s3, s49, s93
	s_cselect_b32 s8, s48, s92
	s_cmp_lg_u32 s29, 1
	s_cbranch_scc1 .Lpn_nh0
	s_and_b32 s9, s2, 8
	s_lshr_b32 s9, s9, 1
	s_xor_b32 s2, s2, s9
.Lpn_nh0:
	s_cmp_lg_u32 s29, 3
	s_cbranch_scc1 .Lpn_keep0
	s_and_b32 s9, s2, 3
	s_lshl_b32 s9, s9, 2
	s_lshr_b32 s10, s2, 2
	s_or_b32 s2, s9, s10
	s_lshr_b32 s9, s38, 3
	s_add_i32 s2, s2, s9
	s_and_b32 s2, s2, 15

.LBB0_385:
	s_lshl_b32 s10, s13, 3
	s_abs_i32 s11, s10
	v_cvt_f32_u32_e32 v128, s11
	s_sub_i32 s39, 0, s11
	s_ashr_i32 s13, s28, 3
	s_add_i32 s13, s37, s13
	v_rcp_iflag_f32_e32 v128, v128
	s_abs_i32 s37, s13
	s_xor_b32 s28, s13, s10
	s_ashr_i32 s28, s28, 31
	v_mul_f32_e32 v128, 0x4f7ffffe, v128
	v_cvt_u32_f32_e32 v128, v128
	s_nop 0
	v_readfirstlane_b32 s40, v128
	s_mul_i32 s39, s39, s40
	s_mul_hi_u32 s39, s40, s39
	s_add_i32 s40, s40, s39
	s_mul_hi_u32 s39, s37, s40
	s_mul_i32 s40, s39, s11
	s_sub_i32 s37, s37, s40
	s_add_i32 s41, s39, 1
	s_sub_i32 s40, s37, s11
	s_cmp_ge_u32 s37, s11
	s_cselect_b32 s39, s41, s39
	s_cselect_b32 s37, s40, s37
	s_add_i32 s40, s39, 1
	s_cmp_ge_u32 s37, s11
	s_cselect_b32 s11, s40, s39
	s_xor_b32 s11, s11, s28
	s_sub_i32 s11, s11, s28
	s_lshl_b32 s28, s11, 3
	s_sub_i32 s12, s12, s28
	s_min_i32 s12, s12, 8
	s_abs_i32 s37, s12
	v_cvt_f32_u32_e32 v128, s37
	s_sub_i32 s39, 0, s37
	s_mul_i32 s11, s11, s10
	s_sub_i32 s10, s13, s11
	v_rcp_iflag_f32_e32 v128, v128
	s_abs_i32 s11, s10
	s_xor_b32 s13, s10, s12
	s_ashr_i32 s13, s13, 31
	v_mul_f32_e32 v128, 0x4f7ffffe, v128
	v_cvt_u32_f32_e32 v128, v128
	s_nop 0
	v_readfirstlane_b32 s40, v128
	s_mul_i32 s39, s39, s40
	s_mul_hi_u32 s39, s40, s39
	s_add_i32 s40, s40, s39
	s_mul_hi_u32 s39, s11, s40
	s_mul_i32 s40, s39, s37
	s_sub_i32 s11, s11, s40
	s_add_i32 s41, s39, 1
	s_sub_i32 s40, s11, s37
	s_cmp_ge_u32 s11, s37
	s_cselect_b32 s39, s41, s39
	s_cselect_b32 s11, s40, s11
	s_add_i32 s40, s39, 1
	s_cmp_ge_u32 s11, s37
	s_cselect_b32 s11, s40, s39
	s_xor_b32 s11, s11, s13
	s_sub_i32 s37, s11, s13
	s_mul_i32 s11, s37, s12
	s_sub_i32 s10, s10, s11
	s_add_i32 s28, s10, s28
	s_and_b64 s[10:11], s[8:9], exec
	s_cselect_b32 s39, s42, 5
	s_cselect_b32 s10, s49, s93
	s_cselect_b32 s11, s48, s92
	s_cmp_lg_u32 s39, 1
	s_cbranch_scc1 .Lpn_nh1
	s_and_b32 s12, s37, 8
	s_lshr_b32 s12, s12, 1
	s_xor_b32 s37, s37, s12
.Lpn_nh1:
	s_cmp_lg_u32 s39, 3
	s_cbranch_scc1 .Lpn_keep1
	s_and_b32 s12, s37, 3
	s_lshl_b32 s12, s12, 2
	s_lshr_b32 s13, s37, 2
	s_or_b32 s37, s12, s13
	s_lshr_b32 s12, s28, 3
	s_add_i32 s37, s37, s12
	s_and_b32 s37, s37, 15
